# code placement: hot loop heads (GEMM K loops, prep/readout loops, scan chunk loop) pinned to 8-byte phase, scan to 64 bytes
# speedup vs baseline: 1.0079x; 1.0006x over previous
.LBB0_231:
	s_or_b64 exec, exec, s[2:3]
	s_add_i32 s8, s8, s66
	s_add_i32 s7, s7, s6
	s_cmpk_lt_i32 s8, 0xaa0
	s_cbranch_scc0 .LBB0_616
	.p2alignl 3, 3212836864

.LBB0_706:
	s_mov_b32 s4, 0xb000
	s_movk_i32 s1, 0x2000
	s_or_b64 exec, exec, s[2:3]
	v_readlane_b32 s0, v207, 0
	v_readlane_b32 s44, v210, 18
	v_readlane_b32 s56, v210, 30
	v_add_u32_e32 v4, s0, v2
	v_ashrrev_i32_e32 v5, 31, v4
	v_lshlrev_b64 v[4:5], 2, v[4:5]
	v_readlane_b32 s57, v210, 31
	v_readlane_b32 s80, v210, 34
	v_readlane_b32 s58, v210, 32
	v_readlane_b32 s59, v210, 33
	v_lshl_add_u64 v[6:7], s[56:57], 0, v[4:5]
	v_readlane_b32 s81, v210, 35
	v_readlane_b32 s2, v207, 3
	global_load_dword v0, v[6:7], off
	v_lshl_add_u64 v[6:7], s[58:59], 0, v[4:5]
	v_lshl_add_u64 v[4:5], s[80:81], 0, v[4:5]
	v_ashrrev_i32_e32 v3, 31, v2
	v_readlane_b32 s3, v207, 4
	global_load_dword v55, v[4:5], off
	s_mov_b32 s0, 0x8000
	v_lshl_add_u64 v[4:5], v[2:3], 2, s[2:3]
	global_load_dword v54, v[6:7], off
	v_lshlrev_b32_e32 v96, 2, v2
	global_load_dword v6, v96, s[2:3]
	global_load_dword v7, v96, s[2:3] offset:1024
	global_load_dword v8, v96, s[2:3] offset:2048
	global_load_dword v9, v96, s[2:3] offset:3072
	v_add_u32_e32 v96, 0x1000, v96
	global_load_dword v10, v96, s[2:3]
	global_load_dword v11, v96, s[2:3] offset:1024
	global_load_dword v12, v96, s[2:3] offset:2048
	global_load_dword v13, v96, s[2:3] offset:3072
	v_add_u32_e32 v96, 0x1000, v96
	global_load_dword v14, v96, s[2:3]
	global_load_dword v15, v96, s[2:3] offset:1024
	global_load_dword v16, v96, s[2:3] offset:2048
	global_load_dword v17, v96, s[2:3] offset:3072
	v_add_u32_e32 v96, 0x1000, v96
	global_load_dword v18, v96, s[2:3]
	global_load_dword v19, v96, s[2:3] offset:1024
	global_load_dword v20, v96, s[2:3] offset:2048
	global_load_dword v21, v96, s[2:3] offset:3072
	v_add_u32_e32 v96, 0x1000, v96
	global_load_dword v22, v96, s[2:3]
	global_load_dword v23, v96, s[2:3] offset:1024
	global_load_dword v24, v96, s[2:3] offset:2048
	global_load_dword v25, v96, s[2:3] offset:3072
	v_add_u32_e32 v96, 0x1000, v96
	global_load_dword v26, v96, s[2:3]
	global_load_dword v27, v96, s[2:3] offset:1024
	global_load_dword v28, v96, s[2:3] offset:2048
	global_load_dword v29, v96, s[2:3] offset:3072
	v_add_u32_e32 v96, 0x1000, v96
	global_load_dword v30, v96, s[2:3]
	global_load_dword v31, v96, s[2:3] offset:1024
	global_load_dword v32, v96, s[2:3] offset:2048
	global_load_dword v33, v96, s[2:3] offset:3072
	v_add_u32_e32 v96, 0x1000, v96
	global_load_dword v34, v96, s[2:3]
	global_load_dword v35, v96, s[2:3] offset:1024
	global_load_dword v36, v96, s[2:3] offset:2048
	global_load_dword v37, v96, s[2:3] offset:3072
	v_add_u32_e32 v96, 0x1000, v96
	global_load_dword v56, v96, s[2:3]
	global_load_dword v57, v96, s[2:3] offset:1024
	global_load_dword v58, v96, s[2:3] offset:2048
	global_load_dword v59, v96, s[2:3] offset:3072
	v_add_u32_e32 v96, 0x1000, v96
	global_load_dword v60, v96, s[2:3]
	global_load_dword v61, v96, s[2:3] offset:1024
	global_load_dword v62, v96, s[2:3] offset:2048
	global_load_dword v63, v96, s[2:3] offset:3072
	v_add_u32_e32 v96, 0x1000, v96
	global_load_dword v64, v96, s[2:3]
	global_load_dword v65, v96, s[2:3] offset:1024
	global_load_dword v66, v96, s[2:3] offset:2048
	global_load_dword v67, v96, s[2:3] offset:3072
	v_add_u32_e32 v96, 0x1000, v96
	global_load_dword v68, v96, s[2:3]
	global_load_dword v69, v96, s[2:3] offset:1024
	global_load_dword v70, v96, s[2:3] offset:2048
	global_load_dword v71, v96, s[2:3] offset:3072
	v_add_u32_e32 v96, 0x1000, v96
	global_load_dword v72, v96, s[2:3]
	global_load_dword v73, v96, s[2:3] offset:1024
	global_load_dword v74, v96, s[2:3] offset:2048
	global_load_dword v75, v96, s[2:3] offset:3072
	v_add_u32_e32 v96, 0x1000, v96
	global_load_dword v76, v96, s[2:3]
	global_load_dword v77, v96, s[2:3] offset:1024
	global_load_dword v78, v96, s[2:3] offset:2048
	global_load_dword v79, v96, s[2:3] offset:3072
	v_add_u32_e32 v96, 0x1000, v96
	global_load_dword v80, v96, s[2:3]
	global_load_dword v81, v96, s[2:3] offset:1024
	global_load_dword v82, v96, s[2:3] offset:2048
	global_load_dword v83, v96, s[2:3] offset:3072
	v_add_u32_e32 v96, 0x1000, v96
	global_load_dword v84, v96, s[2:3]
	global_load_dword v85, v96, s[2:3] offset:1024
	global_load_dword v86, v96, s[2:3] offset:2048
	global_load_dword v87, v96, s[2:3] offset:3072
	s_waitcnt lgkmcnt(0)
	s_barrier
	s_movk_i32 s3, 0x4000
	s_movk_i32 s0, 0x1000
	s_nop 0
	s_mov_b32 s0, 0x9000
	s_nop 0
	s_mov_b32 s0, 0xa000
	s_nop 0
	s_movk_i32 s0, 0x3000
	s_nop 0
	s_mov_b32 s0, 0xc000
	s_nop 0
	s_nop 0
	s_nop 0
	s_movk_i32 s0, 0x5000
	s_nop 0
	s_mov_b32 s0, 0xd000
	s_nop 0
	s_movk_i32 s0, 0x6000
	s_nop 0
	s_mov_b32 s0, 0xe000
	s_nop 0
	s_movk_i32 s0, 0x7000
	s_nop 0
	s_mov_b32 s0, 0xf000
	s_nop 0
	s_nop 0
	s_nop 0
	s_nop 0
	s_nop 0
	s_nop 0
	s_nop 0
	v_readlane_b32 s0, v207, 2
	v_readlane_b32 s48, v210, 22
	v_readlane_b32 s49, v210, 23
	v_add_u32_e32 v4, s0, v2
	v_ashrrev_i32_e32 v5, 31, v4
	v_lshl_add_u64 v[100:101], v[4:5], 2, s[48:49]
	global_load_dword v88, v[100:101], off
	global_load_dword v89, v[100:101], off offset:1024
	s_mov_b32 s2, 0
	s_mov_b32 s0, s97
	v_readlane_b32 s45, v210, 19
	v_readlane_b32 s46, v210, 20
	v_readlane_b32 s47, v210, 21
	v_readlane_b32 s50, v210, 24
	v_readlane_b32 s51, v210, 25
	v_readlane_b32 s52, v210, 26
	v_readlane_b32 s53, v210, 27
	v_readlane_b32 s54, v210, 28
	v_readlane_b32 s55, v210, 29
	v_readlane_b32 s82, v210, 36
	v_readlane_b32 s83, v210, 37
	v_readlane_b32 s84, v210, 38
	v_readlane_b32 s85, v210, 39
	v_readlane_b32 s86, v210, 40
	v_readlane_b32 s87, v210, 41
	v_readlane_b32 s88, v210, 42
	v_readlane_b32 s89, v210, 43
	v_readlane_b32 s90, v210, 44
	v_readlane_b32 s91, v210, 45
	v_readlane_b32 s92, v210, 46
	v_readlane_b32 s93, v210, 47
	v_readlane_b32 s94, v210, 48
	v_readlane_b32 s95, v210, 49
	s_waitcnt vmcnt(0)
	v_mov_b32_e32 v94, 0
	ds_read_b128 v[136:139], v94 offset:0
	ds_read_b128 v[140:143], v94 offset:128
	ds_read_b128 v[144:147], v94 offset:16
	ds_read_b128 v[148:151], v94 offset:144
	ds_read_b128 v[152:155], v94 offset:32
	ds_read_b128 v[156:159], v94 offset:160
	ds_read_b128 v[160:163], v94 offset:48
	ds_read_b128 v[164:167], v94 offset:176
	ds_read_b128 v[184:187], v94 offset:64
	ds_read_b128 v[188:191], v94 offset:192
	ds_read_b128 v[192:195], v94 offset:80
	ds_read_b128 v[196:199], v94 offset:208
	ds_read_b128 v[200:203], v94 offset:96
	ds_read_b128 v[212:215], v94 offset:224
	ds_read_b128 v[216:219], v94 offset:112
	ds_read_b128 v[220:223], v94 offset:240
	s_lshl_b32 s4, s97, 10
	v_lshlrev_b32_e32 v95, 2, v2
	v_add_u32_e32 v95, s4, v95
	.p2alignl 3, 3212836864
.LBB0_707:
	v_mov_b32_e32 v94, s2
	s_waitcnt lgkmcnt(12)
	v_pk_mul_f32 v[90:91], v[136:137], v[6:7]
	v_pk_fma_f32 v[90:91], v[138:139], v[8:9], v[90:91]
	ds_read_b128 v[136:139], v94 offset:512
	v_pk_mul_f32 v[92:93], v[140:141], v[56:57]
	v_pk_fma_f32 v[92:93], v[142:143], v[58:59], v[92:93]
	ds_read_b128 v[140:143], v94 offset:640
	v_pk_fma_f32 v[90:91], v[144:145], v[10:11], v[90:91]
	v_pk_fma_f32 v[90:91], v[146:147], v[12:13], v[90:91]
	ds_read_b128 v[144:147], v94 offset:528
	v_pk_fma_f32 v[92:93], v[148:149], v[60:61], v[92:93]
	v_pk_fma_f32 v[92:93], v[150:151], v[62:63], v[92:93]
	ds_read_b128 v[148:151], v94 offset:656
	s_waitcnt lgkmcnt(12)
	v_pk_fma_f32 v[90:91], v[152:153], v[14:15], v[90:91]
	v_pk_fma_f32 v[90:91], v[154:155], v[16:17], v[90:91]
	ds_read_b128 v[152:155], v94 offset:544
	v_pk_fma_f32 v[92:93], v[156:157], v[64:65], v[92:93]
	v_pk_fma_f32 v[92:93], v[158:159], v[66:67], v[92:93]
	ds_read_b128 v[156:159], v94 offset:672
	v_pk_fma_f32 v[90:91], v[160:161], v[18:19], v[90:91]
	v_pk_fma_f32 v[90:91], v[162:163], v[20:21], v[90:91]
	ds_read_b128 v[160:163], v94 offset:560
	v_pk_fma_f32 v[92:93], v[164:165], v[68:69], v[92:93]
	v_pk_fma_f32 v[92:93], v[166:167], v[70:71], v[92:93]
	ds_read_b128 v[164:167], v94 offset:688
	s_waitcnt lgkmcnt(12)
	v_pk_fma_f32 v[90:91], v[184:185], v[22:23], v[90:91]
	v_pk_fma_f32 v[90:91], v[186:187], v[24:25], v[90:91]
	ds_read_b128 v[184:187], v94 offset:576
	v_pk_fma_f32 v[92:93], v[188:189], v[72:73], v[92:93]
	v_pk_fma_f32 v[92:93], v[190:191], v[74:75], v[92:93]
	ds_read_b128 v[188:191], v94 offset:704
	v_pk_fma_f32 v[90:91], v[192:193], v[26:27], v[90:91]
	v_pk_fma_f32 v[90:91], v[194:195], v[28:29], v[90:91]
	ds_read_b128 v[192:195], v94 offset:592
	v_pk_fma_f32 v[92:93], v[196:197], v[76:77], v[92:93]
	v_pk_fma_f32 v[92:93], v[198:199], v[78:79], v[92:93]
	ds_read_b128 v[196:199], v94 offset:720
	s_waitcnt lgkmcnt(12)
	v_pk_fma_f32 v[90:91], v[200:201], v[30:31], v[90:91]
	v_pk_fma_f32 v[90:91], v[202:203], v[32:33], v[90:91]
	ds_read_b128 v[200:203], v94 offset:608
	v_pk_fma_f32 v[92:93], v[212:213], v[80:81], v[92:93]
	v_pk_fma_f32 v[92:93], v[214:215], v[82:83], v[92:93]
	ds_read_b128 v[212:215], v94 offset:736
	v_pk_fma_f32 v[90:91], v[216:217], v[34:35], v[90:91]
	v_pk_fma_f32 v[90:91], v[218:219], v[36:37], v[90:91]
	ds_read_b128 v[216:219], v94 offset:624
	v_pk_fma_f32 v[92:93], v[220:221], v[84:85], v[92:93]
	v_pk_fma_f32 v[92:93], v[222:223], v[86:87], v[92:93]
	ds_read_b128 v[220:223], v94 offset:752
	s_addk_i32 s2, 0x200
	v_add_f32_e32 v98, v90, v88
	v_add_f32_e32 v99, v92, v89
	v_add_f32_e32 v98, v98, v91
	v_add_f32_e32 v99, v99, v93
	v_mul_f32_e32 v98, 0xbfb8aa3b, v98
	v_mul_f32_e32 v99, 0xbfb8aa3b, v99
	v_exp_f32_e32 v98, v98
	v_exp_f32_e32 v99, v99
	s_nop 0
	v_add_f32_e32 v98, 1.0, v98
	v_add_f32_e32 v99, 1.0, v99
	v_rcp_f32_e32 v98, v98
	v_rcp_f32_e32 v99, v99
	s_nop 0
	v_mul_f32_e32 v98, 0xbf60028a, v98
	v_mul_f32_e32 v99, 0xbf60028a, v99
	v_exp_f32_e32 v98, v98
	v_exp_f32_e32 v99, v99
	s_cmpk_eq_i32 s2, 0x4400
	s_nop 0
	global_store_dword v95, v98, s[14:15]
	global_store_dword v95, v99, s[16:17]
	v_add_u32_e32 v95, 0x400, v95
	s_cbranch_scc0 .LBB0_707
	s_waitcnt lgkmcnt(0)
	v_lshlrev_b64 v[6:7], 2, v[2:3]
	v_lshl_add_u64 v[66:67], s[68:69], 0, v[6:7]
	v_mov_b32_e32 v96, v6
	global_load_dword v8, v96, s[68:69]
	global_load_dword v9, v96, s[68:69] offset:1024
	global_load_dword v10, v96, s[68:69] offset:2048
	global_load_dword v11, v96, s[68:69] offset:3072
	v_add_u32_e32 v96, 0x1000, v96
	global_load_dword v12, v96, s[68:69]
	global_load_dword v13, v96, s[68:69] offset:1024
	global_load_dword v14, v96, s[68:69] offset:2048
	global_load_dword v15, v96, s[68:69] offset:3072
	v_add_u32_e32 v96, 0x1000, v96
	global_load_dword v16, v96, s[68:69]
	global_load_dword v17, v96, s[68:69] offset:1024
	global_load_dword v18, v96, s[68:69] offset:2048
	global_load_dword v19, v96, s[68:69] offset:3072
	v_add_u32_e32 v96, 0x1000, v96
	global_load_dword v20, v96, s[68:69]
	global_load_dword v21, v96, s[68:69] offset:1024
	global_load_dword v22, v96, s[68:69] offset:2048
	global_load_dword v23, v96, s[68:69] offset:3072
	v_add_u32_e32 v96, 0x1000, v96
	global_load_dword v24, v96, s[68:69]
	global_load_dword v25, v96, s[68:69] offset:1024
	global_load_dword v26, v96, s[68:69] offset:2048
	global_load_dword v27, v96, s[68:69] offset:3072
	v_add_u32_e32 v96, 0x1000, v96
	global_load_dword v28, v96, s[68:69]
	global_load_dword v29, v96, s[68:69] offset:1024
	global_load_dword v30, v96, s[68:69] offset:2048
	global_load_dword v31, v96, s[68:69] offset:3072
	v_add_u32_e32 v96, 0x1000, v96
	global_load_dword v32, v96, s[68:69]
	global_load_dword v33, v96, s[68:69] offset:1024
	global_load_dword v34, v96, s[68:69] offset:2048
	global_load_dword v35, v96, s[68:69] offset:3072
	v_add_u32_e32 v96, 0x1000, v96
	global_load_dword v36, v96, s[68:69]
	global_load_dword v37, v96, s[68:69] offset:1024
	global_load_dword v38, v96, s[68:69] offset:2048
	global_load_dword v39, v96, s[68:69] offset:3072
	v_add_u32_e32 v96, 0x1000, v96
	global_load_dword v56, v96, s[68:69]
	global_load_dword v57, v96, s[68:69] offset:1024
	global_load_dword v58, v96, s[68:69] offset:2048
	global_load_dword v59, v96, s[68:69] offset:3072
	v_add_u32_e32 v96, 0x1000, v96
	global_load_dword v60, v96, s[68:69]
	global_load_dword v61, v96, s[68:69] offset:1024
	global_load_dword v62, v96, s[68:69] offset:2048
	global_load_dword v63, v96, s[68:69] offset:3072
	v_add_u32_e32 v96, 0x1000, v96
	global_load_dword v64, v96, s[68:69]
	global_load_dword v65, v96, s[68:69] offset:1024
	global_load_dword v66, v96, s[68:69] offset:2048
	global_load_dword v67, v96, s[68:69] offset:3072
	v_add_u32_e32 v96, 0x1000, v96
	global_load_dword v68, v96, s[68:69]
	global_load_dword v69, v96, s[68:69] offset:1024
	global_load_dword v70, v96, s[68:69] offset:2048
	global_load_dword v71, v96, s[68:69] offset:3072
	v_add_u32_e32 v96, 0x1000, v96
	global_load_dword v72, v96, s[68:69]
	global_load_dword v73, v96, s[68:69] offset:1024
	global_load_dword v74, v96, s[68:69] offset:2048
	global_load_dword v75, v96, s[68:69] offset:3072
	v_add_u32_e32 v96, 0x1000, v96
	global_load_dword v76, v96, s[68:69]
	global_load_dword v77, v96, s[68:69] offset:1024
	global_load_dword v78, v96, s[68:69] offset:2048
	global_load_dword v79, v96, s[68:69] offset:3072
	v_add_u32_e32 v96, 0x1000, v96
	global_load_dword v80, v96, s[68:69]
	global_load_dword v81, v96, s[68:69] offset:1024
	global_load_dword v82, v96, s[68:69] offset:2048
	global_load_dword v83, v96, s[68:69] offset:3072
	v_add_u32_e32 v96, 0x1000, v96
	global_load_dword v84, v96, s[68:69]
	global_load_dword v85, v96, s[68:69] offset:1024
	global_load_dword v86, v96, s[68:69] offset:2048
	global_load_dword v87, v96, s[68:69] offset:3072
	s_mov_b32 s0, 0xc000
	v_readlane_b32 s44, v210, 18
	s_nop 0
	s_nop 0
	s_nop 0
	v_readlane_b32 s52, v210, 26
	s_nop 0
	s_nop 0
	s_nop 0
	v_readlane_b32 s53, v210, 27
	s_nop 0
	s_nop 0
	s_nop 0
	v_lshl_add_u64 v[4:5], v[4:5], 2, s[52:53]
	s_nop 0
	s_nop 0
	s_nop 0
	s_movk_i32 s0, 0x5000
	s_nop 0
	s_mov_b32 s0, 0xd000
	s_nop 0
	s_movk_i32 s0, 0x6000
	s_nop 0
	s_mov_b32 s0, 0xe000
	s_nop 0
	s_movk_i32 s0, 0x7000
	s_nop 0
	s_mov_b32 s0, 0xf000
	s_nop 0
	s_nop 0
	s_nop 0
	s_nop 0
	s_nop 0
	s_nop 0
	s_nop 0
	s_nop 0
	s_nop 0
	s_nop 0
	s_nop 0
	s_nop 0
	global_load_dword v88, v[4:5], off
	global_load_dword v89, v[4:5], off offset:1024
	v_and_b32_e32 v5, 63, v2
	v_ashrrev_i32_e32 v4, 6, v2
	v_readlane_b32 s56, v210, 30
	v_readlane_b32 s57, v210, 31
	v_readlane_b32 s58, v210, 32
	v_readlane_b32 s59, v210, 33
	v_cmp_eq_u32_e32 vcc, 0, v5
	v_ashrrev_i32_e32 v5, 31, v4
	v_readlane_b32 s80, v208, 27
	s_movk_i32 s61, 0x4000
	s_mov_b32 s6, 0
	v_lshl_add_u64 v[4:5], v[4:5], 2, s[24:25]
	v_lshl_add_u64 v[6:7], s[12:13], 0, v[6:7]
	s_movk_i32 s7, 0x100
	v_readlane_b32 s81, v208, 28
	v_readlane_b32 s82, v208, 29
	v_readlane_b32 s83, v208, 30
	v_readlane_b32 s84, v208, 31
	v_readlane_b32 s85, v208, 32
	v_readlane_b32 s86, v208, 33
	v_readlane_b32 s87, v208, 34
	v_readlane_b32 s88, v208, 35
	v_readlane_b32 s89, v208, 36
	v_readlane_b32 s90, v208, 37
	v_readlane_b32 s91, v208, 38
	v_readlane_b32 s92, v208, 39
	v_readlane_b32 s93, v208, 40
	v_readlane_b32 s94, v208, 41
	v_readlane_b32 s95, v208, 42
	s_mov_b32 s56, 0x10000
	s_mov_b32 s57, 0x20000
	s_mov_b32 s58, 0x30000
	s_movk_i32 s59, 0x70
	v_readlane_b32 s45, v210, 19
	v_readlane_b32 s46, v210, 20
	v_readlane_b32 s47, v210, 21
	v_readlane_b32 s48, v210, 22
	v_readlane_b32 s49, v210, 23
	v_readlane_b32 s50, v210, 24
	v_readlane_b32 s51, v210, 25
	v_readlane_b32 s54, v210, 28
	v_readlane_b32 s55, v210, 29
	s_waitcnt vmcnt(0) lgkmcnt(0)
	v_mov_b32_e32 v94, s7
	ds_read_b128 v[136:139], v94 offset:0
	ds_read_b128 v[140:143], v94 offset:128
	ds_read_b128 v[144:147], v94 offset:16
	ds_read_b128 v[148:151], v94 offset:144
	ds_read_b128 v[152:155], v94 offset:32
	ds_read_b128 v[156:159], v94 offset:160
	ds_read_b128 v[160:163], v94 offset:48
	ds_read_b128 v[164:167], v94 offset:176
	ds_read_b128 v[184:187], v94 offset:64
	ds_read_b128 v[188:191], v94 offset:192
	ds_read_b128 v[192:195], v94 offset:80
	ds_read_b128 v[196:199], v94 offset:208
	ds_read_b128 v[200:203], v94 offset:96
	ds_read_b128 v[212:215], v94 offset:224
	ds_read_b128 v[216:219], v94 offset:112
	ds_read_b128 v[220:223], v94 offset:240
	s_lshl_b32 s4, s97, 10
	v_lshlrev_b32_e32 v95, 2, v2
	v_add_u32_e32 v95, s4, v95
	s_mov_b32 s1, 0
	v_mad_i64_i32 v[44:45], s[2:3], s97, v178, v[6:7]
	global_load_dword v42, v[44:45], off
	global_load_dword v43, v[44:45], off offset:1024
	s_add_i32 s8, s97, 1
	v_mad_i64_i32 v[44:45], s[2:3], s8, v178, v[6:7]
	global_load_dword v48, v[44:45], off
	global_load_dword v49, v[44:45], off offset:1024
	s_waitcnt vmcnt(2)
	s_branch .Lrw2_even_entry
	.p2alignl 3, 3212836864

.LBB0_1063:
	s_andn2_b64 vcc, exec, s[0:1]
	s_cbranch_vccnz .LBB0_1071
	v_readlane_b32 s0, v207, 5
	v_readlane_b32 s1, v207, 6
	s_and_b64 s[0:1], s[0:1], exec
	v_readlane_b32 s0, v208, 26
	s_cselect_b32 s0, s0, s97
	s_and_b32 s7, s0, 3
	s_lshr_b32 s6, s0, 2
	s_lshr_b32 s9, s0, 5
	s_lshl_b32 s2, s6, 5
	s_and_b32 s2, s2, 0xc0
	s_and_b32 s3, s6, 1
	v_readlane_b32 s4, v210, 50
	v_readlane_b32 s5, v210, 51
	v_readlane_b32 s52, v210, 32
	v_readlane_b32 s53, v210, 33
	v_readlane_b32 s8, v208, 60
	s_cmp_eq_u32 s3, 0
	s_cselect_b32 s46, s14, s16
	s_cselect_b32 s47, s15, s17
	s_cselect_b32 s48, s18, s20
	s_cselect_b32 s49, s19, s21
	s_cselect_b32 s50, s26, s4
	s_cselect_b32 s51, s27, s5
	s_cselect_b32 s34, 16, -16
	s_cselect_b32 s10, 1, -1
	s_cselect_b32 s54, 0, 0xff
	s_cselect_b32 s55, 0, 0xfff
	s_lshl_b32 s0, s9, 8
	s_add_i32 s0, s0, 0x4000
	s_add_i32 s54, s54, s0
	s_lshl_b32 s0, s9, 12
	s_add_i32 s55, s55, s0
	s_setprio 3
	v_lshrrev_b32_e32 v119, 4, v133
	v_and_b32_e32 v120, 15, v133
	v_and_b32_e32 v121, 12, v120
	v_and_b32_e32 v0, 1, v120
	v_lshl_or_b32 v121, v0, 1, v121
	v_bfe_u32 v0, v120, 1, 1
	v_or_b32_e32 v121, v121, v0
	v_mul_i32_i24_e32 v0, s10, v119
	v_add_u32_e32 v113, s54, v0
	v_add_u32_e32 v117, s55, v0
	v_mul_i32_i24_e32 v0, s10, v121
	v_add_u32_e32 v114, s54, v0
	v_add_u32_e32 v126, s55, v0
	v_and_b32_e32 v0, 8, v120
	v_cmp_ne_u32_e64 s[38:39], 0, v0
	v_and_b32_e32 v0, 4, v120
	v_cmp_ne_u32_e64 s[40:41], 0, v0
	v_and_b32_e32 v0, 1, v120
	v_cmp_ne_u32_e64 s[42:43], 0, v0
	v_and_b32_e32 v0, 2, v120
	v_cmp_ne_u32_e64 s[44:45], 0, v0
	v_lshlrev_b32_e32 v0, 4, v120
	s_lshl_b32 s0, s2, 2
	v_add_u32_e32 v115, s0, v0
	s_lshl_b32 s1, s7, 4
	v_add_u32_e32 v122, s1, v119
	v_lshl_add_u32 v116, v122, 2, s0
	v_mov_b32_e32 v110, v0
	v_lshlrev_b32_e32 v111, 2, v122
	v_lshl_add_u32 v112, v119, 8, v0
	s_lshl_b32 s8, s8, 10
	s_add_u32 s52, s52, s8
	s_addc_u32 s53, s53, 0
	global_load_dwordx4 v[6:9], v115, s[52:53]
	v_mov_b32_e32 v2, 0
	v_mov_b32_e32 v3, 0
	v_mov_b32_e32 v4, 0
	v_mov_b32_e32 v5, 0
	v_mov_b32_e32 v82, 0
	v_mov_b32_e32 v83, 0
	v_mov_b32_e32 v84, 0
	v_mov_b32_e32 v85, 0
	v_mov_b32_e32 v92, 0
	s_mov_b32 s33, 0
	v_mul_u32_u24_e32 v0, 0xf00, v113
	v_lshl_add_u32 v125, v113, 10, v115
	v_add_u32_e32 v0, v0, v115
	v_add_u32_e32 v113, s34, v113
	global_load_dwordx4 v[22:25], v125, s[46:47]
	global_load_dwordx4 v[26:29], v125, s[48:49]
	global_load_dwordx4 v[30:33], v125, s[22:23]
	global_load_dwordx4 v[14:17], v0, s[12:13] offset:1024
	global_load_dwordx4 v[10:13], v0, s[12:13]
	global_load_dwordx4 v[18:21], v0, s[12:13] offset:2048
	s_waitcnt vmcnt(0)
	v_pk_add_f32 v[122:123], v[26:27], -1.0 op_sel_hi:[1,0]
	v_pk_add_f32 v[124:125], v[28:29], -1.0 op_sel_hi:[1,0]
	v_pk_mul_f32 v[118:119], v[30:31], v[26:27]
	v_pk_fma_f32 v[122:123], v[6:7], v[122:123], 1.0 op_sel_hi:[1,1,0]
	v_pk_fma_f32 v[124:125], v[8:9], v[124:125], 1.0 op_sel_hi:[1,1,0]
	v_pk_mul_f32 v[120:121], v[32:33], v[28:29]
	v_pk_mul_f32 v[122:123], v[14:15], v[122:123]
	v_pk_mul_f32 v[124:125], v[16:17], v[124:125]
	ds_write_b128 v112, v[22:25] offset:0
	ds_write_b128 v112, v[30:33] offset:4096
	ds_write_b128 v112, v[10:13] offset:16384
	ds_write_b128 v112, v[18:21] offset:20480
	ds_write_b128 v112, v[118:121] offset:8192
	ds_write_b128 v112, v[122:125] offset:12288
	s_waitcnt lgkmcnt(0)
	v_xor_b32_e32 v112, 0x6000, v112
	v_mul_u32_u24_e32 v0, 0xf00, v113
	v_lshl_add_u32 v125, v113, 10, v115
	v_add_u32_e32 v0, v0, v115
	v_add_u32_e32 v113, s34, v113
	global_load_dwordx4 v[146:149], v125, s[46:47]
	global_load_dwordx4 v[150:153], v125, s[48:49]
	global_load_dwordx4 v[154:157], v125, s[22:23]
	global_load_dwordx4 v[138:141], v0, s[12:13] offset:1024
	global_load_dwordx4 v[134:137], v0, s[12:13]
	global_load_dwordx4 v[142:145], v0, s[12:13] offset:2048
	s_barrier
	.p2alignl 6, 3212836864

.LBB0_1128:
	s_or_b64 exec, exec, s[2:3]
	v_ashrrev_i32_e32 v49, 31, v48
	v_lshlrev_b64 v[54:55], 2, v[48:49]
	v_lshl_add_u64 v[42:43], s[0:1], 0, v[54:55]
	v_mov_b32_e32 v96, v54
	global_load_dword v2, v96, s[0:1]
	global_load_dword v3, v96, s[0:1] offset:1024
	global_load_dword v4, v96, s[0:1] offset:2048
	global_load_dword v5, v96, s[0:1] offset:3072
	v_add_u32_e32 v96, 0x1000, v96
	global_load_dword v6, v96, s[0:1]
	global_load_dword v7, v96, s[0:1] offset:1024
	global_load_dword v8, v96, s[0:1] offset:2048
	global_load_dword v9, v96, s[0:1] offset:3072
	v_add_u32_e32 v96, 0x1000, v96
	global_load_dword v10, v96, s[0:1]
	global_load_dword v11, v96, s[0:1] offset:1024
	global_load_dword v12, v96, s[0:1] offset:2048
	global_load_dword v13, v96, s[0:1] offset:3072
	v_add_u32_e32 v96, 0x1000, v96
	global_load_dword v14, v96, s[0:1]
	global_load_dword v15, v96, s[0:1] offset:1024
	global_load_dword v16, v96, s[0:1] offset:2048
	global_load_dword v17, v96, s[0:1] offset:3072
	v_add_u32_e32 v96, 0x1000, v96
	global_load_dword v18, v96, s[0:1]
	global_load_dword v19, v96, s[0:1] offset:1024
	global_load_dword v20, v96, s[0:1] offset:2048
	global_load_dword v21, v96, s[0:1] offset:3072
	v_add_u32_e32 v96, 0x1000, v96
	global_load_dword v22, v96, s[0:1]
	global_load_dword v23, v96, s[0:1] offset:1024
	global_load_dword v24, v96, s[0:1] offset:2048
	global_load_dword v25, v96, s[0:1] offset:3072
	v_add_u32_e32 v96, 0x1000, v96
	global_load_dword v26, v96, s[0:1]
	global_load_dword v27, v96, s[0:1] offset:1024
	global_load_dword v28, v96, s[0:1] offset:2048
	global_load_dword v29, v96, s[0:1] offset:3072
	v_add_u32_e32 v96, 0x1000, v96
	global_load_dword v30, v96, s[0:1]
	global_load_dword v31, v96, s[0:1] offset:1024
	global_load_dword v32, v96, s[0:1] offset:2048
	global_load_dword v33, v96, s[0:1] offset:3072
	v_add_u32_e32 v96, 0x1000, v96
	global_load_dword v34, v96, s[0:1]
	global_load_dword v35, v96, s[0:1] offset:1024
	global_load_dword v36, v96, s[0:1] offset:2048
	global_load_dword v37, v96, s[0:1] offset:3072
	v_add_u32_e32 v96, 0x1000, v96
	global_load_dword v38, v96, s[0:1]
	global_load_dword v39, v96, s[0:1] offset:1024
	global_load_dword v40, v96, s[0:1] offset:2048
	global_load_dword v41, v96, s[0:1] offset:3072
	v_add_u32_e32 v96, 0x1000, v96
	global_load_dword v58, v96, s[0:1]
	global_load_dword v59, v96, s[0:1] offset:1024
	global_load_dword v60, v96, s[0:1] offset:2048
	global_load_dword v61, v96, s[0:1] offset:3072
	v_add_u32_e32 v96, 0x1000, v96
	global_load_dword v62, v96, s[0:1]
	global_load_dword v63, v96, s[0:1] offset:1024
	global_load_dword v64, v96, s[0:1] offset:2048
	global_load_dword v65, v96, s[0:1] offset:3072
	v_add_u32_e32 v96, 0x1000, v96
	global_load_dword v66, v96, s[0:1]
	global_load_dword v67, v96, s[0:1] offset:1024
	global_load_dword v68, v96, s[0:1] offset:2048
	global_load_dword v69, v96, s[0:1] offset:3072
	v_add_u32_e32 v96, 0x1000, v96
	global_load_dword v70, v96, s[0:1]
	global_load_dword v71, v96, s[0:1] offset:1024
	global_load_dword v72, v96, s[0:1] offset:2048
	global_load_dword v73, v96, s[0:1] offset:3072
	v_add_u32_e32 v96, 0x1000, v96
	global_load_dword v74, v96, s[0:1]
	global_load_dword v75, v96, s[0:1] offset:1024
	global_load_dword v76, v96, s[0:1] offset:2048
	global_load_dword v77, v96, s[0:1] offset:3072
	v_add_u32_e32 v96, 0x1000, v96
	global_load_dword v78, v96, s[0:1]
	global_load_dword v79, v96, s[0:1] offset:1024
	global_load_dword v80, v96, s[0:1] offset:2048
	global_load_dword v81, v96, s[0:1] offset:3072
	s_movk_i32 s2, 0x1000
	s_movk_i32 s3, 0x2000
	s_movk_i32 s2, 0x3000
	s_nop 0
	s_mov_b32 s4, 0xb000
	s_nop 0
	s_movk_i32 s2, 0x5000
	s_nop 0
	v_readlane_b32 s44, v210, 34
	s_nop 0
	s_movk_i32 s2, 0x6000
	s_nop 0
	s_movk_i32 s2, 0x7000
	s_nop 0
	s_mov_b32 s2, 0x8000
	s_nop 0
	s_mov_b32 s2, 0x9000
	s_nop 0
	s_mov_b32 s2, 0xa000
	s_nop 0
	s_mov_b32 s2, 0xc000
	s_nop 0
	s_nop 0
	s_nop 0
	s_mov_b32 s2, 0xd000
	s_nop 0
	s_mov_b32 s2, 0xe000
	s_nop 0
	s_mov_b32 s2, 0xf000
	s_nop 0
	s_nop 0
	s_nop 0
	s_nop 0
	s_nop 0
	s_nop 0
	s_nop 0
	s_nop 0
	s_nop 0
	s_nop 0
	s_nop 0
	s_nop 0
	s_nop 0
	v_add_u32_e32 v46, s7, v48
	v_ashrrev_i32_e32 v47, 31, v46
	v_lshlrev_b64 v[46:47], 2, v[46:47]
	v_readlane_b32 s48, v210, 38
	v_readlane_b32 s49, v210, 39
	v_readlane_b32 s50, v210, 40
	v_readlane_b32 s51, v210, 41
	v_lshl_add_u64 v[50:51], s[48:49], 0, v[46:47]
	global_load_dword v82, v[50:51], off
	v_lshl_add_u64 v[46:47], s[50:51], 0, v[46:47]
	global_load_dword v83, v[46:47], off
	v_readlane_b32 s45, v210, 35
	v_readlane_b32 s46, v210, 36
	v_readlane_b32 s47, v210, 37
	v_readlane_b32 s52, v210, 42
	v_readlane_b32 s53, v210, 43
	v_readlane_b32 s54, v210, 44
	v_readlane_b32 s55, v210, 45
	v_readlane_b32 s56, v210, 46
	v_readlane_b32 s57, v210, 47
	v_readlane_b32 s58, v210, 48
	v_readlane_b32 s59, v210, 49
	s_ashr_i32 s35, s34, 31
	v_readlane_b32 s44, v210, 50
	s_lshl_b64 s[2:3], s[34:35], 11
	s_lshl_b64 s[36:37], s[34:35], 4
	s_lshl_b64 s[38:39], s[34:35], 10
	v_readlane_b32 s46, v210, 52
	v_readlane_b32 s47, v210, 53
	s_add_u32 s2, s46, s2
	s_addc_u32 s3, s47, s3
	s_mul_i32 s9, s34, 0xf00
	v_ashrrev_i32_e32 v52, 6, v48
	v_lshl_add_u64 v[48:49], v[48:49], 1, s[2:3]
	v_readlane_b32 s2, v208, 22
	s_mul_hi_i32 s5, s34, 0xf00
	s_add_u32 s2, s2, s9
	s_addc_u32 s3, s69, s5
	v_lshl_add_u64 v[50:51], s[2:3], 0, v[54:55]
	s_add_u32 s2, s24, s36
	v_ashrrev_i32_e32 v53, 31, v52
	v_readlane_b32 s45, v210, 51
	s_addc_u32 s3, s25, s37
	v_lshl_add_u64 v[56:57], s[38:39], 0, v[54:55]
	s_mov_b32 s4, 0
	v_lshl_add_u64 v[52:53], v[52:53], 2, s[2:3]
	v_lshl_add_u64 v[54:55], s[26:27], 0, v[56:57]
	v_lshl_add_u64 v[56:57], s[44:45], 0, v[56:57]
	s_mov_b64 s[2:3], 0
	s_waitcnt lgkmcnt(0)
	s_barrier
	v_readlane_b32 s48, v210, 54
	v_readlane_b32 s49, v210, 55
	v_readlane_b32 s50, v210, 56
	v_readlane_b32 s51, v210, 57
	v_readlane_b32 s52, v210, 58
	v_readlane_b32 s53, v210, 59
	v_readlane_b32 s54, v210, 60
	v_readlane_b32 s55, v210, 61
	v_readlane_b32 s56, v210, 62
	v_readlane_b32 s57, v210, 63
	v_readlane_b32 s58, v209, 0
	v_readlane_b32 s59, v209, 1
	s_mov_b64 s[36:37], 0xf00
	s_mov_b64 s[38:39], 0x800
	v_mov_b32_e32 v94, 0
	ds_read_b128 v[136:139], v94 offset:0
	ds_read_b128 v[140:143], v94 offset:16
	ds_read_b128 v[144:147], v94 offset:32
	ds_read_b128 v[148:151], v94 offset:48
	ds_read_b128 v[152:155], v94 offset:64
	ds_read_b128 v[156:159], v94 offset:80
	ds_read_b128 v[160:163], v94 offset:96
	ds_read_b128 v[164:167], v94 offset:112
	ds_read_b128 v[184:187], v94 offset:128
	ds_read_b128 v[188:191], v94 offset:144
	ds_read_b128 v[192:195], v94 offset:160
	ds_read_b128 v[196:199], v94 offset:176
	ds_read_b128 v[200:203], v94 offset:192
	ds_read_b128 v[212:215], v94 offset:208
	ds_read_b128 v[216:219], v94 offset:224
	ds_read_b128 v[220:223], v94 offset:240
	v_lshl_add_u64 v[96:97], v[54:55], 0, s[2:3]
	global_load_dword v84, v[96:97], off
	v_lshl_add_u64 v[96:97], v[56:57], 0, s[2:3]
	global_load_dword v85, v[96:97], off
	global_load_dword v86, v[52:53], off
	global_load_dword v87, v[50:51], off
	s_add_u32 s2, s2, 0x400
	s_addc_u32 s3, s3, 0
	v_lshl_add_u64 v[52:53], v[52:53], 0, 16
	v_lshl_add_u64 v[50:51], v[50:51], 0, s[36:37]
	v_lshl_add_u64 v[96:97], v[54:55], 0, s[2:3]
	global_load_dword v100, v[96:97], off
	v_lshl_add_u64 v[96:97], v[56:57], 0, s[2:3]
	global_load_dword v101, v[96:97], off
	global_load_dword v102, v[52:53], off
	global_load_dword v103, v[50:51], off
	s_add_u32 s2, s2, 0x400
	s_addc_u32 s3, s3, 0
	v_lshl_add_u64 v[52:53], v[52:53], 0, 16
	v_lshl_add_u64 v[50:51], v[50:51], 0, s[36:37]
	s_waitcnt vmcnt(4)
	s_branch .Lro_even_entry
	.p2alignl 3, 3212836864

.LBB0_1184:
	s_or_b64 exec, exec, s[0:1]
	v_readlane_b32 s0, v207, 0
	v_readlane_b32 s1, v207, 1
	s_and_b64 s[0:1], s[0:1], exec
	s_movk_i32 s0, 0x440
	s_cselect_b32 s0, 0x400, s0
	s_cmp_ge_i32 s97, s0
	s_waitcnt lgkmcnt(0)
	s_barrier
	v_writelane_b32 v207, s0, 2
	s_cbranch_scc1 .LBB0_1188
	v_readlane_b32 s36, v210, 50
	v_readlane_b32 s44, v210, 58
	v_readlane_b32 s45, v210, 59
	v_readlane_b32 s46, v210, 60
	v_readlane_b32 s47, v210, 61
	v_readlane_b32 s48, v210, 62
	v_readlane_b32 s49, v210, 63
	v_readlane_b32 s50, v209, 0
	v_readlane_b32 s51, v209, 1
	v_readlane_b32 s44, v210, 2
	s_lshl_b32 s0, s60, 1
	v_readlane_b32 s42, v210, 56
	v_readlane_b32 s52, v210, 10
	v_readlane_b32 s53, v210, 11
	v_readlane_b32 s43, v210, 57
	s_add_u32 s0, s42, s0
	v_readlane_b32 s54, v210, 12
	v_readlane_b32 s55, v210, 13
	v_readlane_b32 s56, v210, 14
	v_readlane_b32 s57, v210, 15
	v_readlane_b32 s58, v210, 16
	v_readlane_b32 s59, v210, 17
	v_readlane_b32 s52, v208, 58
	s_addc_u32 s1, s43, 0
	s_lshl_b32 s2, s66, 7
	v_readlane_b32 s3, v208, 16
	s_mov_b32 s4, s97
	s_mov_b32 s61, 0x30000
	s_mov_b32 s63, 0x20000
	s_mov_b32 s10, 0x10000
	s_mov_b32 s62, 0x12000
	s_mov_b32 s57, 0x13000
	s_mov_b32 s54, 0x18000
	s_mov_b32 s55, 0x19000
	s_mov_b32 s72, 0x1a000
	s_mov_b32 s73, 0x1b000
	s_mov_b32 s74, 0x21000
	s_mov_b32 s75, 0x22000
	s_mov_b32 s76, 0x23000
	s_mov_b32 s77, 0x28000
	s_mov_b32 s78, 0x29000
	s_mov_b32 s79, 0x2a000
	s_mov_b32 s58, 0x2b000
	s_mov_b32 s56, 0x31000
	s_mov_b32 s97, 0x32000
	s_mov_b32 s9, 0x33000
	s_mov_b32 s69, 0x38000
	s_mov_b32 s60, 0x3a000
	s_mov_b32 s67, 0x39000
	v_readlane_b32 s70, v208, 62
	v_readlane_b32 s53, v208, 59
	s_mov_b32 s33, 0x3b000
	v_readlane_b32 s59, v207, 2
	v_readlane_b32 s37, v210, 51
	v_readlane_b32 s38, v210, 52
	v_readlane_b32 s39, v210, 53
	v_readlane_b32 s40, v210, 54
	v_readlane_b32 s41, v210, 55
	v_readlane_b32 s45, v210, 3
	v_readlane_b32 s46, v210, 4
	v_readlane_b32 s47, v210, 5
	v_readlane_b32 s48, v210, 6
	v_readlane_b32 s49, v210, 7
	v_readlane_b32 s50, v210, 8
	v_readlane_b32 s51, v210, 9
	v_readlane_b32 s4, v209, 2
	s_and_b32 s5, s4, 7
	s_lshr_b32 s4, s4, 3
	s_lshl_b32 s5, s5, 6
	s_or_b32 s4, s4, s5
	s_lshl_b32 s3, s4, 7
	.p2alignl 3, 3212836864

.LBB0_1296:
	s_or_b64 exec, exec, s[0:1]
	v_readlane_b32 s0, v207, 0
	v_readlane_b32 s1, v207, 1
	s_and_b64 s[0:1], s[0:1], exec
	s_movk_i32 s0, 0x1000
	s_cselect_b32 s2, s0, 0x1100
	s_cmp_ge_i32 s97, s2
	s_waitcnt lgkmcnt(0)
	s_barrier
	s_cbranch_scc1 .LBB0_1300
	s_mov_b64 s[8:9], s[42:43]
	v_readlane_b32 s36, v210, 50
	s_lshl_b32 s0, s60, 1
	v_readlane_b32 s44, v210, 58
	v_readlane_b32 s45, v210, 59
	s_add_u32 s0, s44, s0
	v_readlane_b32 s38, v210, 52
	v_readlane_b32 s39, v210, 53
	v_readlane_b32 s50, v209, 0
	v_readlane_b32 s51, v209, 1
	s_addc_u32 s1, s45, 0
	s_lshl_b32 s3, s66, 7
	v_readlane_b32 s4, v208, 16
	s_mov_b32 s5, s97
	v_readlane_b32 s37, v210, 51
	v_readlane_b32 s40, v210, 54
	v_readlane_b32 s41, v210, 55
	v_readlane_b32 s42, v210, 56
	v_readlane_b32 s43, v210, 57
	v_readlane_b32 s46, v210, 60
	v_readlane_b32 s47, v210, 61
	v_readlane_b32 s48, v210, 62
	v_readlane_b32 s49, v210, 63
	v_readlane_b32 s5, v209, 2
	s_and_b32 s6, s5, 1
	s_lshl_b32 s6, s6, 8
	s_bfe_u32 s7, s5, 0x20001
	s_lshl_b32 s7, s7, 3
	s_or_b32 s6, s6, s7
	s_bfe_u32 s7, s5, 0x30003
	s_or_b32 s6, s6, s7
	s_lshr_b32 s7, s5, 6
	s_lshl_b32 s7, s7, 5
	s_or_b32 s5, s6, s7
	s_lshl_b32 s4, s5, 7
	.p2alignl 3, 3212836864

.Ldma9_join_b:
	s_barrier
	s_add_i32 s3, s3, 2
	v_lshl_add_u64 v[134:135], v[134:135], 0, s[28:29]
	s_andn2_b64 vcc, exec, s[4:5]
	v_lshl_add_u64 v[136:137], v[136:137], 0, s[30:31]
	s_cbranch_vccz .LBB0_1354
	.p2alignl 3, 3212836864
